# down-GEMM phase: workgroups that own a context split-K unit run it BEFORE their main tile, so the residual epilogues of the two groups no longer burst at the same time (on top of v33)
# baseline (speedup 1.0000x reference)
.LBB0_1230:
	s_or_b64 exec, exec, s[2:3]
	s_mul_hi_u32 s0, s24, 0x580000
	s_mul_i32 s24, s24, 0x580000
	v_readlane_b32 s1, v249, 62
	s_add_u32 s26, s1, s24
	v_readlane_b32 s1, v249, 63
	s_addc_u32 s27, s1, s0
	v_readlane_b32 s0, v255, 14
	v_readlane_b32 s1, v255, 15
	s_and_b64 s[0:1], exec, s[0:1]
	s_movk_i32 s0, 0x800
	s_cselect_b32 s14, s0, 0x2000
	v_readlane_b32 s0, v251, 45
	v_mov_b32_e32 v10, v198
	v_readlane_b32 s1, v251, 46
	s_waitcnt lgkmcnt(0)
	s_barrier
	s_mov_b32 s99, 0
	s_branch .LBB0_1254
.Ldn_main:
	v_readlane_b32 s0, v251, 45
	v_readlane_b32 s1, v251, 46
	v_mov_b32_e32 v10, v198
	s_nop 1
	s_andn2_b64 vcc, exec, s[0:1]
	v_readfirstlane_b32 s0, v10
	s_cbranch_vccnz .LBB0_1254
	v_lshlrev_b32_e32 v0, 4, v10
	v_add_u32_e32 v2, 0x2000, v0
	v_ashrrev_i32_e32 v3, 31, v2
	v_lshrrev_b32_e32 v3, 22, v3
	v_add_u32_e32 v3, v2, v3
	v_ashrrev_i32_e32 v6, 10, v3
	v_mul_i32_i24_e32 v3, 0x400, v6
	v_sub_u32_e32 v2, v2, v3
	v_lshrrev_b32_e32 v3, 4, v2
	v_bitop3_b32 v2, v3, v2, 32 bitop3:0x6c
	v_ashrrev_i32_e32 v3, 31, v2
	v_lshrrev_b32_e32 v3, 26, v3
	v_add_u32_e32 v3, v2, v3
	v_ashrrev_i32_e32 v7, 6, v3
	v_and_b32_e32 v3, 0xc0, v3
	v_sub_u32_e32 v2, v2, v3
	v_ashrrev_i16_sdwa v2, v201, sext(v2) dst_sel:DWORD dst_unused:UNUSED_PAD src0_sel:DWORD src1_sel:BYTE_0
	v_bfe_i32 v9, v2, 0, 16
	v_bfe_i32 v2, v10, 27, 1
	v_lshrrev_b32_e32 v2, 22, v2
	v_add_u32_e32 v2, v0, v2
	v_and_b32_e32 v2, 0xfffffc00, v2
	v_sub_u32_e32 v0, v0, v2
	v_lshrrev_b32_e32 v2, 4, v0
	v_ashrrev_i32_e32 v3, 31, v10
	v_bitop3_b32 v0, v2, v0, 32 bitop3:0x6c
	v_lshrrev_b32_e32 v3, 26, v3
	v_lshlrev_b32_e32 v4, 3, v6
	v_ashrrev_i32_e32 v2, 31, v0
	v_add_u32_e32 v3, v10, v3
	v_and_b32_e32 v4, 0xfffff0, v4
	v_lshrrev_b32_e32 v2, 26, v2
	v_ashrrev_i32_e32 v12, 6, v3
	v_add_u32_e32 v4, v7, v4
	s_movk_i32 s3, 0xb00
	v_lshlrev_b32_e32 v5, 5, v6
	v_add_u32_e32 v2, v0, v2
	v_lshlrev_b32_e32 v3, 3, v12
	v_mul_lo_u32 v4, v4, s3
	v_and_b32_e32 v8, 32, v5
	v_ashrrev_i32_e32 v11, 6, v2
	v_and_b32_e32 v3, 0xfffff0, v3
	s_ashr_i32 s2, s0, 6
	v_or_b32_e32 v4, v4, v8
	v_add_u32_e32 v3, v11, v3
	v_and_b32_e32 v2, 0xc0, v2
	v_readlane_b32 s4, v252, 29
	s_ashr_i32 s1, s0, 8
	s_lshl_b32 s22, s2, 10
	v_add_lshl_u32 v130, v4, v9, 1
	v_mul_lo_u32 v3, v3, s3
	v_lshlrev_b32_e32 v4, 5, v12
	v_sub_u32_e32 v0, v0, v2
	s_mul_i32 s3, s4, 0x160000
	v_and_b32_e32 v13, 32, v4
	v_ashrrev_i16_sdwa v0, v201, sext(v0) dst_sel:DWORD dst_unused:UNUSED_PAD src0_sel:DWORD src1_sel:BYTE_0
	s_add_u32 s8, s26, s3
	s_mul_hi_i32 s3, s4, 0x160000
	v_or_b32_e32 v3, v3, v13
	v_bfe_i32 v14, v0, 0, 16
	s_addc_u32 s9, s27, s3
	s_add_i32 s23, s22, 0
	v_add_lshl_u32 v0, v3, v14, 1
	s_add_i32 m0, s23, 0x10000
	v_mov_b32_e32 v131, v1
	global_load_lds_dwordx4 v0, s[8:9]
	s_add_i32 m0, s23, 0x12000
	s_add_u32 s4, s8, 0xb0000
	global_load_lds_dwordx4 v130, s[8:9]
	s_addc_u32 s5, s9, 0
	s_add_i32 m0, s23, 0x14000
	s_add_i32 s24, s23, 0x2000
	global_load_lds_dwordx4 v0, s[4:5]
	s_add_i32 m0, s23, 0x16000
	s_add_i32 s25, s23, 0x4000
	global_load_lds_dwordx4 v130, s[4:5]
	v_readlane_b32 s4, v252, 38
	s_mov_b32 m0, s23
	v_readlane_b32 s5, v252, 39
	s_add_i32 s28, s23, 0x6000
	s_cmp_eq_u32 s1, 1
	v_lshl_add_u64 v[2:3], s[8:9], 0, v[0:1]
	s_cselect_b64 s[42:43], -1, 0
	s_cmp_lg_u32 s1, 1
	global_load_lds_dwordx4 v0, s[4:5]
	s_mov_b32 m0, s24
	v_lshl_add_u64 v[4:5], s[8:9], 0, v[130:131]
	global_load_lds_dwordx4 v130, s[4:5]
	v_readlane_b32 s4, v252, 40
	s_mov_b32 m0, s25
	v_readlane_b32 s5, v252, 41
	s_nop 4
	global_load_lds_dwordx4 v0, s[4:5]
	s_mov_b32 m0, s28
	s_nop 0
	global_load_lds_dwordx4 v130, s[4:5]
	s_cbranch_scc1 .LBB0_1233
	s_barrier

.LBB0_1254:
	s_cmp_lg_u32 s99, 0
	s_cbranch_scc0 .Ldn_first
	s_andn2_b64 s[0:1], exec, s[44:45]
	s_cbranch_scc1 .LBB0_187
	s_cmp_eq_u32 s99, 2
	s_cbranch_scc0 .Ldn_end_nosk
	v_readlane_b32 s4, v255, 40
	v_readlane_b32 s5, v255, 41
	v_readlane_b32 s6, v255, 42
	v_readlane_b32 s7, v255, 43
	v_readlane_b32 s8, v255, 44
	v_readlane_b32 s9, v255, 45
	v_readlane_b32 s10, v255, 46
	v_readlane_b32 s12, v255, 47
	v_readlane_b32 s13, v255, 48
	v_readlane_b32 s16, v255, 49
	v_readlane_b32 s17, v255, 50
	v_readlane_b32 s18, v255, 51
	v_readlane_b32 s19, v255, 52
	v_readlane_b32 s22, v255, 53
	v_readlane_b32 s25, v255, 54
	v_readlane_b32 s40, v255, 55
	v_readlane_b32 s41, v255, 56
	v_readlane_b32 s42, v255, 57
	v_readlane_b32 s43, v255, 58
	v_readlane_b32 s45, v255, 59
	v_readlane_b32 s46, v255, 60
	v_readlane_b32 s47, v255, 61
	v_readlane_b32 s48, v255, 62
	v_readlane_b32 s50, v255, 63
	s_nop 4
	s_branch .LBB0_1271
.Ldn_end_nosk:
	v_mov_b32_e32 v2, v198
	v_readfirstlane_b32 s5, v2
	s_branch .LBB0_1271
.Ldn_first:
	s_mov_b32 s99, 1
	s_andn2_b64 vcc, exec, s[44:45]
	s_cbranch_vccnz .Ldn_main
	v_readlane_b32 s0, v253, 5
	v_mov_b32_e32 v2, v198
	v_readlane_b32 s1, v253, 6
	s_andn2_b64 vcc, exec, s[0:1]
	v_readfirstlane_b32 s5, v2
	s_cbranch_vccnz .Ldn_main
	v_writelane_b32 v255, s12, 28
	v_writelane_b32 v255, s13, 29
	v_writelane_b32 v255, s16, 30
	v_writelane_b32 v255, s17, 31
	v_writelane_b32 v255, s42, 32
	v_writelane_b32 v255, s43, 33
	v_writelane_b32 v255, s44, 34
	v_writelane_b32 v255, s45, 35
	v_writelane_b32 v255, s46, 36
	v_writelane_b32 v255, s47, 37
	v_writelane_b32 v255, s48, 38
	v_writelane_b32 v255, s50, 39
	v_lshlrev_b32_e32 v0, 4, v2
	v_add_u32_e32 v3, 0x2000, v0
	v_ashrrev_i32_e32 v4, 31, v3
	v_lshrrev_b32_e32 v4, 22, v4
	v_add_u32_e32 v4, v3, v4
	v_ashrrev_i32_e32 v4, 10, v4
	v_mul_i32_i24_e32 v5, 0x400, v4
	v_sub_u32_e32 v3, v3, v5
	v_lshrrev_b32_e32 v5, 4, v3
	v_bitop3_b32 v3, v5, v3, 32 bitop3:0x6c
	v_ashrrev_i32_e32 v5, 31, v3
	v_lshrrev_b32_e32 v5, 26, v5
	v_add_u32_e32 v5, v3, v5
	v_lshlrev_b32_e32 v7, 3, v4
	v_lshrrev_b32_e32 v6, 6, v5
	v_and_b32_e32 v7, 0xfffff0, v7
	v_and_b32_e32 v5, 0xc0, v5
	v_add_u32_e32 v6, v6, v7
	s_movk_i32 s4, 0xb00
	v_sub_u32_e32 v3, v3, v5
	v_mul_lo_u32 v6, v6, s4
	v_lshlrev_b32_e32 v4, 5, v4
	v_ashrrev_i16_sdwa v3, v201, sext(v3) dst_sel:DWORD dst_unused:UNUSED_PAD src0_sel:DWORD src1_sel:BYTE_0
	v_and_or_b32 v4, v4, 32, v6
	v_bfe_i32 v3, v3, 0, 16
	v_add_lshl_u32 v130, v4, v3, 1
	v_bfe_i32 v3, v2, 27, 1
	v_lshrrev_b32_e32 v3, 22, v3
	v_add_u32_e32 v3, v0, v3
	v_and_b32_e32 v3, 0xfffffc00, v3
	v_sub_u32_e32 v0, v0, v3
	v_lshrrev_b32_e32 v3, 4, v0
	v_ashrrev_i32_e32 v5, 31, v2
	v_readlane_b32 s0, v253, 9
	v_bitop3_b32 v0, v3, v0, 32 bitop3:0x6c
	v_lshrrev_b32_e32 v5, 26, v5
	s_add_u32 s0, s26, s0
	v_readlane_b32 s1, v253, 10
	v_ashrrev_i32_e32 v3, 31, v0
	v_add_u32_e32 v5, v2, v5
	s_addc_u32 s1, s27, s1
	v_readlane_b32 s2, v253, 14
	v_lshrrev_b32_e32 v3, 26, v3
	v_ashrrev_i32_e32 v5, 6, v5
	v_readlane_b32 s3, v253, 15
	s_add_u32 s2, s0, s2
	v_add_u32_e32 v3, v0, v3
	v_lshlrev_b32_e32 v6, 3, v5
	s_addc_u32 s3, s1, s3
	s_ashr_i32 s0, s5, 6
	v_lshrrev_b32_e32 v4, 6, v3
	v_and_b32_e32 v6, 0xfffff0, v6
	v_and_b32_e32 v3, 0xc0, v3
	s_ashr_i32 s1, s5, 8
	s_lshl_b32 s7, s0, 10
	v_add_u32_e32 v4, v4, v6
	v_sub_u32_e32 v0, v0, v3
	s_add_u32 s8, s2, 0xb0000
	v_mul_lo_u32 v4, v4, s4
	v_lshlrev_b32_e32 v5, 5, v5
	v_ashrrev_i16_sdwa v0, v201, sext(v0) dst_sel:DWORD dst_unused:UNUSED_PAD src0_sel:DWORD src1_sel:BYTE_0
	s_addc_u32 s9, s3, 0
	v_and_or_b32 v4, v5, 32, v4
	v_bfe_i32 v0, v0, 0, 16
	s_add_i32 s13, s7, 0
	v_add_lshl_u32 v0, v4, v0, 1
	s_add_i32 m0, s13, 0x10000
	s_add_i32 s28, s13, 0x2000
	global_load_lds_dwordx4 v0, s[2:3]
	s_add_i32 m0, s13, 0x12000
	s_add_i32 s29, s13, 0x4000
	global_load_lds_dwordx4 v130, s[2:3]
	s_add_i32 m0, s13, 0x14000
	s_add_i32 s30, s13, 0x6000
	global_load_lds_dwordx4 v0, s[8:9]
	s_add_i32 m0, s13, 0x16000
	s_cmp_lg_u32 s1, 1
	global_load_lds_dwordx4 v130, s[8:9]
	v_readlane_b32 s8, v253, 16
	s_mov_b32 m0, s13
	v_readlane_b32 s9, v253, 17
	s_nop 4
	global_load_lds_dwordx4 v0, s[8:9]
	s_mov_b32 m0, s28
	s_nop 0
	global_load_lds_dwordx4 v130, s[8:9]
	v_readlane_b32 s8, v253, 18
	s_mov_b32 m0, s29
	v_readlane_b32 s9, v253, 19
	s_nop 4
	global_load_lds_dwordx4 v0, s[8:9]
	s_mov_b32 m0, s30
	s_nop 0
	global_load_lds_dwordx4 v130, s[8:9]
	s_cbranch_scc1 .LBB0_1258
	s_barrier

.LBB0_1270:
	v_lshlrev_b32_e32 v0, 2, v133
	v_lshl_or_b32 v0, s36, 8, v0
	s_lshl_b32 s0, s14, 2
	v_readlane_b32 s1, v254, 46
	v_or_b32_e32 v130, s31, v0
	s_add_u32 s0, s1, s0
	v_readlane_b32 s1, v254, 48
	v_ashrrev_i32_e32 v131, 31, v130
	s_addc_u32 s1, s1, 0
	v_lshlrev_b64 v[130:131], 2, v[130:131]
	v_lshl_add_u64 v[142:143], s[0:1], 0, v[130:131]
	s_barrier
	global_load_dwordx4 v[134:137], v[142:143], off
	global_load_dwordx4 v[138:141], v[142:143], off offset:64
	global_load_dwordx4 v[148:151], v[142:143], off offset:512
	global_load_dwordx4 v[152:155], v[142:143], off offset:576
	s_ashr_i32 s5, s4, 31
	s_ashr_i32 s7, s6, 31
	s_lshl_b64 s[0:1], s[6:7], 20
	s_lshl_b64 s[2:3], s[4:5], 21
	v_readlane_b32 s4, v251, 39
	v_readlane_b32 s5, v251, 40
	s_add_u32 s0, s4, s0
	s_addc_u32 s1, s5, s1
	s_add_u32 s0, s0, s2
	s_addc_u32 s1, s1, s3
	s_ashr_i32 s2, s12, 31
	v_or_b32_e32 v132, s12, v132
	v_mov_b32_e32 v133, s2
	v_lshlrev_b64 v[132:133], 12, v[132:133]
	v_lshl_add_u64 v[132:133], s[0:1], 0, v[132:133]
	s_brev_b32 s0, 63
	v_lshl_add_u64 v[130:131], v[132:133], 0, v[130:131]
	s_mov_b32 s1, -1
	v_lshl_add_u64 v[156:157], v[130:131], 0, s[0:1]
	s_brev_b32 s0, 63
	v_add_co_u32_e32 v158, vcc, s0, v130
	s_mov_b32 s0, 0xfc010000
	s_nop 0
	v_addc_co_u32_e32 v159, vcc, -1, v131, vcc
	v_add_co_u32_e32 v160, vcc, s0, v130
	s_mov_b32 s0, 0xfc011000
	s_nop 0
	v_addc_co_u32_e32 v161, vcc, -1, v131, vcc
	v_add_co_u32_e32 v162, vcc, s0, v130
	s_mov_b32 s0, 0xfc020000
	s_nop 0
	v_addc_co_u32_e32 v163, vcc, -1, v131, vcc
	v_add_co_u32_e32 v164, vcc, s0, v130
	s_mov_b32 s0, 0xfc021000
	s_nop 0
	v_addc_co_u32_e32 v165, vcc, -1, v131, vcc
	v_add_co_u32_e32 v166, vcc, s0, v130
	s_mov_b32 s0, 0xfc030000
	s_nop 0
	v_addc_co_u32_e32 v167, vcc, -1, v131, vcc
	v_readlane_b32 s30, v254, 4
	v_readlane_b32 s34, v254, 6
	v_readlane_b32 s31, v254, 5
	v_readlane_b32 s35, v254, 7
	s_waitcnt vmcnt(0)
	v_pk_mul_f32 v[146:147], v[136:137], 0.5 op_sel_hi:[1,0]
	v_pk_mul_f32 v[144:145], v[134:135], 0.5 op_sel_hi:[1,0]
	v_pk_mul_f32 v[136:137], v[148:149], 0.5 op_sel_hi:[1,0]
	v_pk_mul_f32 v[142:143], v[140:141], 0.5 op_sel_hi:[1,0]
	v_pk_mul_f32 v[140:141], v[138:139], 0.5 op_sel_hi:[1,0]
	v_pk_mul_f32 v[138:139], v[150:151], 0.5 op_sel_hi:[1,0]
	v_pk_mul_f32 v[134:135], v[154:155], 0.5 op_sel_hi:[1,0]
	v_pk_mul_f32 v[132:133], v[152:153], 0.5 op_sel_hi:[1,0]
	v_pk_mul_f32 v[128:129], v[128:129], v[146:147]
	v_pk_mul_f32 v[126:127], v[126:127], v[144:145]
	v_pk_mul_f32 v[82:83], v[82:83], v[136:137]
	v_pk_mul_f32 v[124:125], v[124:125], v[142:143]
	v_pk_mul_f32 v[122:123], v[122:123], v[140:141]
	v_pk_mul_f32 v[104:105], v[104:105], v[138:139]
	v_pk_mul_f32 v[102:103], v[102:103], v[136:137]
	v_pk_mul_f32 v[100:101], v[100:101], v[134:135]
	v_pk_mul_f32 v[98:99], v[98:99], v[132:133]
	v_pk_mul_f32 v[120:121], v[120:121], v[146:147]
	v_pk_mul_f32 v[118:119], v[118:119], v[144:145]
	v_pk_mul_f32 v[116:117], v[116:117], v[142:143]
	v_pk_mul_f32 v[114:115], v[114:115], v[140:141]
	v_pk_mul_f32 v[96:97], v[96:97], v[138:139]
	v_pk_mul_f32 v[94:95], v[94:95], v[136:137]
	v_pk_mul_f32 v[92:93], v[92:93], v[134:135]
	v_pk_mul_f32 v[90:91], v[90:91], v[132:133]
	v_pk_mul_f32 v[112:113], v[112:113], v[146:147]
	v_pk_mul_f32 v[110:111], v[110:111], v[144:145]
	v_pk_mul_f32 v[108:109], v[108:109], v[142:143]
	v_pk_mul_f32 v[106:107], v[106:107], v[140:141]
	v_pk_mul_f32 v[84:85], v[84:85], v[138:139]
	global_store_dwordx4 v[158:159], v[126:129], off
	global_store_dwordx4 v[156:157], v[122:125], off offset:64
	global_store_dwordx4 v[156:157], v[102:105], off offset:512
	global_store_dwordx4 v[156:157], v[98:101], off offset:576
	global_store_dwordx4 v[160:161], v[118:121], off
	global_store_dwordx4 v[162:163], v[114:117], off offset:-4032
	global_store_dwordx4 v[162:163], v[94:97], off offset:-3584
	global_store_dwordx4 v[162:163], v[90:93], off offset:-3520
	global_store_dwordx4 v[164:165], v[110:113], off
	global_store_dwordx4 v[166:167], v[106:109], off offset:-4032
	global_store_dwordx4 v[166:167], v[82:85], off offset:-3584
	v_pk_mul_f32 v[76:77], v[76:77], v[134:135]
	v_pk_mul_f32 v[74:75], v[74:75], v[132:133]
	v_add_co_u32_e32 v82, vcc, s0, v130
	global_store_dwordx4 v[166:167], v[74:77], off offset:-3520
	s_nop 0
	v_addc_co_u32_e32 v83, vcc, -1, v131, vcc
	v_pk_mul_f32 v[76:77], v[88:89], v[146:147]
	v_pk_mul_f32 v[74:75], v[86:87], v[144:145]
	s_mov_b32 s0, 0xfc031000
	global_store_dwordx4 v[82:83], v[74:77], off
	v_pk_mul_f32 v[68:69], v[68:69], v[134:135]
	v_pk_mul_f32 v[66:67], v[66:67], v[132:133]
	v_pk_mul_f32 v[74:75], v[78:79], v[140:141]
	v_add_co_u32_e32 v78, vcc, s0, v130
	s_mov_b32 s0, 0xfc080000
	s_nop 0
	v_addc_co_u32_e32 v79, vcc, -1, v131, vcc
	global_store_dwordx4 v[78:79], v[66:69], off offset:-3520
	v_pk_mul_f32 v[64:65], v[64:65], v[146:147]
	v_pk_mul_f32 v[62:63], v[62:63], v[144:145]
	v_add_co_u32_e32 v66, vcc, s0, v130
	s_mov_b32 s0, 0xfc081000
	s_nop 0
	v_addc_co_u32_e32 v67, vcc, -1, v131, vcc
	global_store_dwordx4 v[66:67], v[62:65], off
	v_pk_mul_f32 v[48:49], v[48:49], v[138:139]
	v_pk_mul_f32 v[46:47], v[46:47], v[136:137]
	v_add_co_u32_e32 v62, vcc, s0, v130
	s_mov_b32 s0, 0xfc090000
	s_nop 0
	v_addc_co_u32_e32 v63, vcc, -1, v131, vcc
	global_store_dwordx4 v[62:63], v[46:49], off offset:-3584
	v_pk_mul_f32 v[44:45], v[44:45], v[134:135]
	v_pk_mul_f32 v[42:43], v[42:43], v[132:133]
	v_add_co_u32_e32 v46, vcc, s0, v130
	global_store_dwordx4 v[62:63], v[42:45], off offset:-3520
	s_nop 0
	v_addc_co_u32_e32 v47, vcc, -1, v131, vcc
	v_pk_mul_f32 v[44:45], v[56:57], v[146:147]
	v_pk_mul_f32 v[42:43], v[54:55], v[144:145]
	s_mov_b32 s0, 0xfc091000
	global_store_dwordx4 v[46:47], v[42:45], off
	v_add_co_u32_e32 v46, vcc, s0, v130
	v_pk_mul_f32 v[32:33], v[32:33], v[138:139]
	s_nop 0
	v_addc_co_u32_e32 v47, vcc, -1, v131, vcc
	v_pk_mul_f32 v[30:31], v[30:31], v[136:137]
	s_mov_b32 s0, 0xfc0a0000
	global_store_dwordx4 v[46:47], v[30:33], off offset:-3584
	v_pk_mul_f32 v[28:29], v[28:29], v[134:135]
	v_pk_mul_f32 v[26:27], v[26:27], v[132:133]
	v_add_co_u32_e32 v30, vcc, s0, v130
	global_store_dwordx4 v[46:47], v[26:29], off offset:-3520
	s_nop 0
	v_addc_co_u32_e32 v31, vcc, -1, v131, vcc
	v_pk_mul_f32 v[28:29], v[40:41], v[146:147]
	v_pk_mul_f32 v[26:27], v[38:39], v[144:145]
	s_mov_b32 s0, 0xfc0a1000
	global_store_dwordx4 v[30:31], v[26:29], off
	v_add_co_u32_e32 v30, vcc, s0, v130
	v_pk_mul_f32 v[16:17], v[16:17], v[138:139]
	s_nop 0
	v_addc_co_u32_e32 v31, vcc, -1, v131, vcc
	v_pk_mul_f32 v[14:15], v[14:15], v[136:137]
	s_mov_b32 s0, 0xfc0b0000
	global_store_dwordx4 v[30:31], v[14:17], off offset:-3584
	v_pk_mul_f32 v[12:13], v[12:13], v[134:135]
	v_pk_mul_f32 v[10:11], v[10:11], v[132:133]
	v_add_co_u32_e32 v14, vcc, s0, v130
	global_store_dwordx4 v[30:31], v[10:13], off offset:-3520
	s_nop 0
	v_addc_co_u32_e32 v15, vcc, -1, v131, vcc
	v_pk_mul_f32 v[12:13], v[24:25], v[146:147]
	v_pk_mul_f32 v[10:11], v[22:23], v[144:145]
	s_mov_b32 s0, 0xfc0b1000
	global_store_dwordx4 v[14:15], v[10:13], off
	v_add_co_u32_e32 v14, vcc, s0, v130
	v_pk_mul_f32 v[76:77], v[80:81], v[142:143]
	v_pk_mul_f32 v[72:73], v[72:73], v[138:139]
	v_pk_mul_f32 v[70:71], v[70:71], v[136:137]
	v_pk_mul_f32 v[60:61], v[60:61], v[142:143]
	v_pk_mul_f32 v[58:59], v[58:59], v[140:141]
	v_pk_mul_f32 v[44:45], v[52:53], v[142:143]
	v_pk_mul_f32 v[42:43], v[50:51], v[140:141]
	v_pk_mul_f32 v[28:29], v[36:37], v[142:143]
	v_pk_mul_f32 v[26:27], v[34:35], v[140:141]
	v_pk_mul_f32 v[12:13], v[20:21], v[142:143]
	v_pk_mul_f32 v[10:11], v[18:19], v[140:141]
	v_addc_co_u32_e32 v15, vcc, -1, v131, vcc
	v_pk_mul_f32 v[8:9], v[8:9], v[138:139]
	v_pk_mul_f32 v[6:7], v[6:7], v[136:137]
	v_pk_mul_f32 v[4:5], v[4:5], v[134:135]
	v_pk_mul_f32 v[2:3], v[2:3], v[132:133]
	global_store_dwordx4 v[78:79], v[74:77], off offset:-4032
	global_store_dwordx4 v[78:79], v[70:73], off offset:-3584
	global_store_dwordx4 v[62:63], v[58:61], off offset:-4032
	global_store_dwordx4 v[46:47], v[42:45], off offset:-4032
	global_store_dwordx4 v[30:31], v[26:29], off offset:-4032
	global_store_dwordx4 v[14:15], v[10:13], off offset:-4032
	global_store_dwordx4 v[14:15], v[6:9], off offset:-3584
	global_store_dwordx4 v[14:15], v[2:5], off offset:-3520
	s_waitcnt vmcnt(0)
	s_barrier
	v_writelane_b32 v255, s4, 40
	v_writelane_b32 v255, s5, 41
	v_writelane_b32 v255, s6, 42
	v_writelane_b32 v255, s7, 43
	v_writelane_b32 v255, s8, 44
	v_writelane_b32 v255, s9, 45
	v_writelane_b32 v255, s10, 46
	v_writelane_b32 v255, s12, 47
	v_writelane_b32 v255, s13, 48
	v_writelane_b32 v255, s16, 49
	v_writelane_b32 v255, s17, 50
	v_writelane_b32 v255, s18, 51
	v_writelane_b32 v255, s19, 52
	v_writelane_b32 v255, s22, 53
	v_writelane_b32 v255, s25, 54
	v_writelane_b32 v255, s40, 55
	v_writelane_b32 v255, s41, 56
	v_writelane_b32 v255, s42, 57
	v_writelane_b32 v255, s43, 58
	v_writelane_b32 v255, s45, 59
	v_writelane_b32 v255, s46, 60
	v_writelane_b32 v255, s47, 61
	v_writelane_b32 v255, s48, 62
	v_writelane_b32 v255, s50, 63
	v_readlane_b32 s12, v255, 28
	v_readlane_b32 s13, v255, 29
	v_readlane_b32 s16, v255, 30
	v_readlane_b32 s17, v255, 31
	v_readlane_b32 s42, v255, 32
	v_readlane_b32 s43, v255, 33
	v_readlane_b32 s44, v255, 34
	v_readlane_b32 s45, v255, 35
	v_readlane_b32 s46, v255, 36
	v_readlane_b32 s47, v255, 37
	v_readlane_b32 s48, v255, 38
	v_readlane_b32 s50, v255, 39
	s_nop 4
	s_mov_b32 s99, 2
	s_branch .Ldn_main
